# v44: v43 + the two layer-1 pre-norm phases write-through with flat barriers
# baseline (speedup 1.0000x reference)
.LBB0_2462:
	s_cmp_lt_i32 s59, 15
	s_barrier
	s_cbranch_scc1 .LBB0_2516
	s_waitcnt vmcnt(0)
	s_barrier
	s_and_saveexec_b64 s[2:3], s[0:1]
	s_cbranch_execz .LBB0_2515
	s_waitcnt vmcnt(0) lgkmcnt(0)
	v_mov_b32_e32 v241, 0
	v_lshlrev_b32_e64 v254, 8, s31
	v_mov_b32_e32 v247, 1
	v_mov_b32_e32 v246, 0x3600
	global_atomic_add v248, v246, v247, s[60:61] sc0
	buffer_inv sc1

.LBB0_3217:
	s_cmp_lt_i32 s59, 23
	s_barrier
	s_cbranch_scc1 .LBB0_3271
	s_waitcnt vmcnt(0)
	s_barrier
	s_and_saveexec_b64 s[2:3], s[0:1]
	s_cbranch_execz .LBB0_3270
	s_waitcnt vmcnt(0) lgkmcnt(0)
	v_mov_b32_e32 v241, 0
	v_lshlrev_b32_e64 v254, 8, s31
	v_mov_b32_e32 v247, 1
	v_mov_b32_e32 v246, 0x3600
	global_atomic_add v248, v246, v247, s[60:61] sc0
	buffer_inv sc1
